# adds: scan phase units assigned statically (unit = vcu + k*G) instead of four atomic work queues (no atomic fetch, LDS broadcast, barriers or store drain between units)
# speedup vs baseline: 1.0041x; 1.0025x over previous
.LBB0_678:
	v_writelane_b32 v255, s90, 8
	v_writelane_b32 v255, s90, 9
	v_writelane_b32 v255, s90, 10
	v_writelane_b32 v255, s90, 11
	s_cmp_lt_i32 s92, 4
	s_cselect_b64 s[0:1], -1, 0
	s_cmp_gt_i32 s93, 3
	s_cselect_b64 s[4:5], -1, 0
	s_and_b64 s[0:1], s[0:1], s[4:5]
	s_andn2_b64 vcc, exec, s[0:1]
	s_cbranch_vccnz .LBB0_996
	s_add_u32 s0, s86, 0x1dd00000
	s_addc_u32 s1, s87, 0
	s_add_u32 s20, s86, 0x200000
	s_addc_u32 s21, s87, 0
	s_add_u32 s4, s86, 0x500000
	s_addc_u32 s5, s87, 0
	s_add_u32 s37, s84, 0x4200000
	v_writelane_b32 v254, s92, 43
	s_addc_u32 s51, s85, 0
	s_cmp_lg_u32 s33, 3
	v_writelane_b32 v254, s93, 44
	v_writelane_b32 v254, s90, 45
	s_cselect_b64 s[6:7], -1, 0
	s_cmpk_gt_u32 s94, 0xff
	v_writelane_b32 v254, s91, 46
	s_cselect_b64 s[8:9], -1, 0
	s_lshl_b32 s10, s33, 4
	v_writelane_b32 v254, s10, 47
	s_and_b32 s10, s10, 0x3fffffe0
	s_lshl_b32 s3, s33, 5
	s_lshl_b32 s12, s10, 1
	s_and_b32 s95, s3, 32
	s_mov_b32 s27, s94
	s_add_i32 s94, s12, 0
	s_add_u32 s12, s72, 0x3000
	s_addc_u32 s13, s73, 0
	v_writelane_b32 v254, s12, 48
	s_mov_b32 s11, 0
	v_mov_b32_e32 v50, 0
	v_writelane_b32 v254, s13, 49
	s_add_u32 s12, s72, 0x6000
	s_addc_u32 s13, s73, 0
	v_writelane_b32 v254, s12, 50
	s_movk_i32 s58, 0x110
	s_movk_i32 s59, 0x800
	v_writelane_b32 v254, s13, 51
	s_add_u32 s12, s72, 0x9000
	s_addc_u32 s13, s73, 0
	s_add_u32 s50, s86, 0x24000000
	v_writelane_b32 v254, s12, 52
	s_addc_u32 s90, s87, 0
	s_sub_i32 s89, s10, 64
	v_writelane_b32 v254, s13, 53
	s_lshl_b32 s12, s89, 2
	s_add_i32 s92, s12, 0
	s_lshl_b32 s12, s95, 2
	s_add_i32 s93, s12, 0
	s_add_i32 s92, s92, 0x20e00
	s_add_i32 s93, s93, 0x1bc00
	s_cmpk_gt_u32 s27, 0xbf
	s_cselect_b64 s[12:13], -1, 0
	s_cmp_lt_u32 s27, 64
	s_cselect_b64 s[28:29], -1, 0
	s_and_b64 s[14:15], s[28:29], exec
	s_cselect_b32 s16, 0, 32
	s_cmp_eq_u32 s33, 1
	s_cselect_b32 s17, 32, 0
	s_lshl_b32 s14, s17, 2
	s_add_i32 s23, s14, 0
	s_add_i32 s22, s23, 0x20c00
	s_add_i32 s23, s23, 0x20d00
	s_lshl_b32 s24, s17, 1
	s_cmp_lg_u32 s33, 2
	s_cselect_b64 s[30:31], -1, 0
	s_lshl_b32 s14, s33, 12
	s_and_b32 s34, s14, 0x1000
	v_writelane_b32 v254, s27, 54
	s_bfe_u32 s14, s27, 0x10006
	s_lshr_b32 s91, s27, 7
	v_writelane_b32 v254, s14, 55
	s_mulk_i32 s14, 0x2200
	s_add_i32 s27, s14, 0
	s_mul_i32 s14, s91, 0x2200
	s_add_i32 s15, 0, 0x23d40
	s_lshl_b32 s25, s91, 2
	s_lshl_b32 s26, s91, 6
	s_add_i32 s27, s27, 0xf400
	s_add_i32 s14, s14, 0
	s_mov_b32 s36, 0xbfb8aa3b
	s_add_i32 s60, 0, 0x20f00
	s_movk_i32 s61, 0x90
	s_mov_b32 s62, 0x5040100
	s_add_i32 s63, 0, 0x17c00
	s_add_i32 s64, 0, 0x1fc00
	s_add_i32 s65, 0, 0x20efc
	s_lshl_b32 s38, s34, 2
	v_mov_b32_e32 v1, s15
	v_mov_b32_e32 v145, 0xfc00
	s_lshl_b32 s40, s10, 2
	s_branch .LBB0_682

.LBB0_682:
	v_readlane_b32 s42, v255, 8
	s_mov_b64 s[34:35], -1
	s_add_i32 s10, s42, s88
	v_writelane_b32 v255, s10, 8
	s_cmpk_gt_i32 s42, 0xff
	s_cbranch_scc1 .LBB0_681
	v_mov_b32_e32 v151, v0
	s_and_b64 vcc, exec, s[6:7]
	v_and_b32_e32 v150, 31, v151
	s_cbranch_vccz .LBB0_753
	s_mov_b64 s[44:45], 0
	s_and_b64 vcc, exec, s[8:9]
	s_mov_b64 s[34:35], 0
	s_cbranch_vccnz .LBB0_754
	v_bfe_u32 v153, v151, 5, 1
	v_lshlrev_b32_e32 v152, 2, v153
	s_and_b64 vcc, exec, s[44:45]
	s_cbranch_vccnz .LBB0_755

.LBB0_759:
	v_readlane_b32 s56, v255, 9
	s_mov_b64 s[0:1], -1
	s_add_i32 s6, s56, s88
	v_writelane_b32 v255, s6, 9
	s_cmpk_gt_i32 s56, 0xff
	s_cbranch_scc1 .LBB0_758
	s_ashr_i32 s48, s56, 5
	s_ashr_i32 s49, s48, 31
	s_bfe_u32 s63, s56, 0x30002
	v_mov_b32_e32 v101, v0
	s_lshl_b64 s[52:53], s[48:49], 11
	v_mov_b32_e32 v5, s53
	s_lshl_b32 s34, s63, 7
	v_cmp_lt_i32_e32 vcc, s27, v101
	s_and_saveexec_b64 s[0:1], vcc
	s_xor_b64 s[6:7], exec, s[0:1]
	s_cbranch_execz .LBB0_770
	v_cmp_lt_u32_e64 s[0:1], s50, v101
	s_and_saveexec_b64 s[8:9], s[0:1]
	s_xor_b64 s[8:9], exec, s[8:9]
	s_cbranch_execz .LBB0_767
	s_lshl_b64 s[0:1], s[48:49], 18
	s_add_u32 s0, s14, s0
	s_addc_u32 s1, s15, s1
	s_lshl_b32 s35, s34, 2
	s_add_u32 s0, s0, s35
	v_lshlrev_b32_e32 v22, 2, v101
	s_addc_u32 s1, s1, 0
	v_add_u32_e32 v2, 0xfffffd80, v22
	v_lshl_add_u64 v[6:7], v[2:3], 2, s[0:1]
	v_cmp_gt_u32_e64 s[0:1], s51, v101
	s_nop 1
	v_cndmask_b32_e64 v2, 0, v98, s[0:1]
	v_cndmask_b32_e64 v85, 0, v7, s[0:1]
	v_cndmask_b32_e64 v84, 0, v6, s[0:1]
	v_mov_b64_e32 v[14:15], v[2:3]

.LBB0_868:
	v_readlane_b32 s8, v255, 10
	s_mov_b64 s[6:7], -1
	s_add_i32 s9, s8, s88
	v_writelane_b32 v255, s9, 10
	s_cmpk_gt_i32 s8, 0xff
	s_cbranch_scc1 .LBB0_867
	s_and_b32 s47, s8, 1
	s_ashr_i32 s34, s8, 1
	s_lshl_b32 s8, s47, 2
	s_ashr_i32 s35, s34, 31
	s_add_i32 s45, s91, s8
	s_lshl_b32 s8, s34, 3
	v_readlane_b32 s48, v254, 9
	s_lshl_b64 s[6:7], s[34:35], 2
	s_add_i32 s34, s45, s8
	v_readlane_b32 s52, v254, 13
	v_readlane_b32 s53, v254, 14
	v_readlane_b32 s54, v254, 15
	v_readlane_b32 s55, v254, 16
	v_readlane_b32 s56, v254, 17
	v_readlane_b32 s57, v254, 18
	v_readlane_b32 s58, v254, 19
	v_readlane_b32 s59, v254, 20
	v_mov_b32_e32 v130, v0
	s_ashr_i32 s35, s34, 31
	v_readlane_b32 s60, v254, 21
	v_readlane_b32 s61, v254, 22
	v_readlane_b32 s62, v254, 23
	v_readlane_b32 s63, v254, 24
	s_mov_b64 s[52:53], s[56:57]
	s_lshl_b64 s[8:9], s[34:35], 14
	v_bfe_u32 v131, v130, 5, 1
	s_lshl_b64 s[34:35], s[34:35], 16
	s_mov_b64 s[54:55], s[58:59]
	s_add_u32 s34, s54, s34
	v_or_b32_e32 v2, s3, v131
	v_lshlrev_b32_e32 v132, 2, v130
	s_addc_u32 s35, s55, s35
	v_lshlrev_b32_e32 v134, 9, v2
	v_and_b32_e32 v138, 0x7c, v132
	v_lshlrev_b32_e32 v136, 7, v2
	v_lshl_add_u64 v[2:3], s[34:35], 0, v[134:135]
	v_lshlrev_b32_e32 v134, 2, v138
	s_waitcnt vmcnt(2)
	v_lshl_add_u64 v[106:107], v[2:3], 0, v[134:135]
	v_lshl_add_u32 v18, s47, 9, v130
	v_add_co_u32_e32 v26, vcc, s37, v106
	v_ashrrev_i32_e32 v19, 31, v18
	s_nop 0
	v_addc_co_u32_e32 v27, vcc, 0, v107, vcc
	v_lshl_add_u64 v[20:21], v[18:19], 2, s[18:19]
	v_add_co_u32_e32 v22, vcc, s37, v20
	global_load_dwordx4 v[14:17], v[106:107], off nt
	global_load_dwordx4 v[10:13], v[106:107], off offset:1024 nt
	global_load_dwordx4 v[6:9], v[106:107], off offset:2048 nt
	global_load_dwordx4 v[2:5], v[106:107], off offset:3072 nt
	v_addc_co_u32_e32 v23, vcc, 0, v21, vcc
	global_load_dword v116, v[22:23], off
	global_load_dword v117, v[20:21], off
	s_add_u32 s6, s6, 0x4000
	s_addc_u32 s7, s7, 0
	s_lshl_b64 s[34:35], s[6:7], 11
	v_readlane_b32 s49, v254, 10
	s_add_u32 s48, s28, s34
	s_addc_u32 s49, s29, s35
	v_lshlrev_b64 v[30:31], 1, v[18:19]
	v_lshl_add_u64 v[32:33], s[48:49], 0, v[30:31]
	global_load_ushort v118, v[32:33], off
	global_load_dwordx4 v[22:25], v[26:27], off offset:1024 nt
	global_load_dwordx4 v[18:21], v[26:27], off offset:2048 nt
	s_add_u32 s48, s12, s34
	s_addc_u32 s49, s13, s35
	v_lshl_add_u64 v[90:91], s[48:49], 0, v[30:31]
	global_load_ushort v133, v[90:91], off
	v_add_co_u32_e32 v28, vcc, s38, v106
	s_add_u32 s34, s30, s34
	s_nop 0
	v_addc_co_u32_e32 v29, vcc, 0, v107, vcc
	s_addc_u32 s35, s31, s35
	v_lshl_add_u64 v[92:93], s[34:35], 0, v[30:31]
	v_add_co_u32_e32 v30, vcc, s37, v32
	v_and_b32_e32 v157, 0x7f, v130
	s_nop 0
	v_addc_co_u32_e32 v31, vcc, 0, v33, vcc
	global_load_ushort v134, v[92:93], off
	global_load_ushort v140, v[92:93], off offset:2048
	global_load_ushort v141, v[30:31], off
	global_load_ushort v142, v[30:31], off offset:2048
	global_load_ushort v143, v[90:91], off offset:2048
	global_load_ushort v145, v[32:33], off offset:2048
	global_load_dwordx4 v[78:81], v[28:29], off offset:-4096 nt
	global_load_dwordx4 v[74:77], v[28:29], off nt
	global_load_dwordx4 v[70:73], v[28:29], off offset:1024 nt
	global_load_dwordx4 v[66:69], v[28:29], off offset:2048 nt
	v_add_co_u32_e32 v30, vcc, s39, v106
	v_and_or_b32 v132, v132, s44, v157
	s_nop 0
	v_addc_co_u32_e32 v31, vcc, 0, v107, vcc
	v_add_co_u32_e32 v32, vcc, s40, v106
	v_lshl_add_u32 v132, v132, 2, 0
	s_nop 0
	v_addc_co_u32_e32 v33, vcc, 0, v107, vcc
	v_add_co_u32_e32 v108, vcc, s41, v106
	global_load_dwordx4 v[82:85], v[28:29], off offset:3072 nt
	global_load_dwordx4 v[34:37], v[32:33], off offset:-4096 nt
	global_load_dwordx4 v[86:89], v[26:27], off offset:3072 nt
	global_load_dwordx4 v[62:65], v[30:31], off offset:1024 nt
	global_load_dwordx4 v[58:61], v[30:31], off offset:2048 nt
	global_load_dwordx4 v[54:57], v[30:31], off offset:3072 nt
	global_load_dwordx4 v[50:53], v[32:33], off nt
	global_load_dwordx4 v[46:49], v[32:33], off offset:1024 nt
	global_load_dwordx4 v[42:45], v[32:33], off offset:2048 nt
	global_load_dwordx4 v[38:41], v[32:33], off offset:3072 nt
	v_addc_co_u32_e32 v109, vcc, 0, v107, vcc
	v_add_co_u32_e32 v90, vcc, s37, v90
	v_and_b32_e32 v144, 63, v130
	s_nop 0
	v_addc_co_u32_e32 v91, vcc, 0, v91, vcc
	s_waitcnt vmcnt(30)
	v_add_co_u32_e32 v114, vcc, s25, v106
	global_load_ushort v146, v[90:91], off
	s_nop 0
	v_addc_co_u32_e32 v115, vcc, 0, v107, vcc
	v_add_co_u32_e32 v92, vcc, s37, v92
	global_load_dwordx4 v[30:33], v[108:109], off offset:1024 nt
	global_load_dwordx4 v[26:29], v[108:109], off offset:2048 nt
	v_addc_co_u32_e32 v93, vcc, 0, v93, vcc
	global_load_ushort v147, v[92:93], off
	global_load_ushort v148, v[92:93], off offset:2048
	global_load_ushort v149, v[90:91], off offset:2048
	global_load_dwordx4 v[110:113], v[114:115], off offset:-4096 nt
	global_load_dwordx4 v[102:105], v[114:115], off nt
	global_load_dwordx4 v[98:101], v[114:115], off offset:1024 nt
	global_load_dwordx4 v[94:97], v[114:115], off offset:2048 nt
	s_nop 0
	global_load_dwordx4 v[90:93], v[114:115], off offset:3072 nt
	v_lshlrev_b32_e32 v130, 4, v130
	v_and_b32_e32 v130, 0x1f0, v130
	s_mov_b32 s46, 0
	v_readlane_b32 s50, v254, 11
	v_readlane_b32 s51, v254, 12
	s_mov_b64 s[56:57], s[60:61]
	s_mov_b64 s[58:59], s[62:63]
	s_waitcnt vmcnt(35)
	v_sub_f32_e32 v114, v116, v117
	v_mul_f32_e32 v114, 0x3fb8aa3b, v114
	v_exp_f32_e32 v116, v114
	v_add_co_u32_e32 v114, vcc, s42, v106
	v_add_f32_e32 v116, 1.0, v116
	v_rcp_f32_e32 v150, v116
	s_waitcnt vmcnt(34)
	v_lshlrev_b32_e32 v116, 16, v118
	v_max_f32_e32 v116, v116, v116
	v_med3_f32 v116, v116, s43, v139
	v_addc_co_u32_e32 v115, vcc, 0, v107, vcc
	v_mul_f32_e32 v116, 0xbfb8aa3b, v116
	global_load_dwordx4 v[126:129], v[108:109], off offset:3072 nt
	s_nop 0
	global_load_dwordx4 v[106:109], v[114:115], off nt
	v_exp_f32_e32 v151, v116
	global_load_dwordx4 v[122:125], v[114:115], off offset:1024 nt
	global_load_dwordx4 v[118:121], v[114:115], off offset:2048 nt
	s_nop 0
	global_load_dwordx4 v[114:117], v[114:115], off offset:3072 nt
	s_waitcnt vmcnt(36)
	v_lshlrev_b32_e32 v133, 16, v133
	v_mul_f32_e32 v153, 0xbfb8aa3b, v133
	v_exp_f32_e32 v153, v153
	v_add_f32_e32 v151, 1.0, v151
	s_waitcnt vmcnt(31)
	v_lshlrev_b32_e32 v143, 16, v143
	s_waitcnt vmcnt(30)
	v_lshlrev_b32_e32 v145, 16, v145
	v_max_f32_e32 v145, v145, v145
	v_med3_f32 v145, v145, s43, v139
	v_mul_f32_e32 v145, 0xbfb8aa3b, v145
	v_add_f32_e32 v153, 1.0, v153
	v_exp_f32_e32 v145, v145
	v_rcp_f32_e32 v153, v153
	v_lshlrev_b32_e32 v141, 16, v141
	v_rcp_f32_e32 v151, v151
	v_add_f32_e32 v145, 1.0, v145
	v_mul_f32_e32 v133, v153, v133
	v_rcp_f32_e32 v145, v145
	v_mul_f32_e32 v153, 0xbfb8aa3b, v143
	v_max_f32_e32 v141, v141, v141
	v_exp_f32_e32 v153, v153
	v_med3_f32 v141, v141, s43, v139
	v_mul_f32_e32 v141, 0xbfb8aa3b, v141
	v_sub_f32_e32 v152, 1.0, v150
	v_exp_f32_e32 v141, v141
	v_fma_f32 v151, v152, v151, v150
	v_fma_f32 v145, v152, v145, v150
	v_sub_f32_e32 v157, 1.0, v151
	ds_write2st64_b32 v132, v151, v145 offset1:2
	v_add_f32_e32 v151, 1.0, v153
	v_rcp_f32_e32 v151, v151
	v_add_f32_e32 v141, 1.0, v141
	v_rcp_f32_e32 v141, v141
	v_lshlrev_b32_e32 v134, 16, v134
	v_mul_f32_e32 v143, v151, v143
	ds_write2st64_b32 v132, v133, v143 offset0:64 offset1:66
	v_lshlrev_b32_e32 v133, 16, v140
	ds_write2st64_b32 v132, v134, v133 offset0:96 offset1:98
	v_fma_f32 v133, v152, v141, v150
	v_lshlrev_b32_e32 v141, 16, v142
	v_max_f32_e32 v141, v141, v141
	v_med3_f32 v141, v141, s43, v139
	v_mul_f32_e32 v141, 0xbfb8aa3b, v141
	v_exp_f32_e32 v141, v141
	v_sub_f32_e32 v145, 1.0, v145
	s_waitcnt vmcnt(15)
	v_lshlrev_b32_e32 v134, 16, v146
	s_waitcnt vmcnt(10)
	v_lshlrev_b32_e32 v143, 16, v149
	ds_write2st64_b32 v132, v157, v145 offset0:32 offset1:34
	v_mul_f32_e32 v140, 0xbfb8aa3b, v134
	v_add_f32_e32 v141, 1.0, v141
	v_mul_f32_e32 v145, 0xbfb8aa3b, v143
	v_exp_f32_e32 v140, v140
	v_rcp_f32_e32 v141, v141
	v_exp_f32_e32 v145, v145
	v_sub_f32_e32 v142, 1.0, v133
	v_add_f32_e32 v140, 1.0, v140
	v_fmac_f32_e32 v150, v152, v141
	v_add_f32_e32 v141, 1.0, v145
	v_rcp_f32_e32 v140, v140
	v_rcp_f32_e32 v141, v141
	ds_write2st64_b32 v132, v133, v150 offset0:4 offset1:6
	v_sub_f32_e32 v133, 1.0, v150
	v_mul_f32_e32 v134, v140, v134
	ds_write2st64_b32 v132, v142, v133 offset0:36 offset1:38
	v_mul_f32_e32 v133, v141, v143
	v_lshlrev_b32_e32 v140, 16, v147
	ds_write2st64_b32 v132, v134, v133 offset0:68 offset1:70
	v_lshlrev_b32_e32 v133, 16, v148
	v_cmp_lt_i32_e32 vcc, v155, v156
	ds_write2st64_b32 v132, v140, v133 offset0:100 offset1:102
	v_add_u32_e32 v134, s24, v130
	v_cndmask_b32_e32 v132, v154, v155, vcc
	v_add_u32_e32 v146, s26, v130
	v_add_u32_e32 v130, s27, v131
	v_lshlrev_b32_e32 v145, 2, v132
	v_cmp_gt_u32_e32 vcc, 32, v144
	v_lshl_add_u32 v147, v130, 2, 0
	s_waitcnt lgkmcnt(0)
	s_barrier
	s_branch .LBB0_875

.LBB0_881:
	v_readlane_b32 s69, v255, 11
	s_mov_b64 s[0:1], -1
	s_add_i32 s4, s69, s88
	v_writelane_b32 v255, s4, 11
	s_cmpk_gt_i32 s69, 0x287
	s_cbranch_scc1 .LBB0_880
	s_cmpk_lt_i32 s69, 0x200
	s_cbranch_scc0 .LBB0_932
	s_and_b32 s15, s69, 3
	s_ashr_i32 s36, s69, 2
	s_lshl_b32 s10, s15, 3
	s_add_i32 s14, s33, s10
	s_lshl_b32 s0, s36, 5
	s_add_i32 s0, s14, s0
	s_ashr_i32 s37, s36, 31
	s_ashr_i32 s1, s0, 31
	v_readlane_b32 s52, v254, 9
	s_waitcnt vmcnt(4)
	v_mov_b32_e32 v164, v0
	s_lshl_b64 s[4:5], s[36:37], 2
	s_lshl_b64 s[6:7], s[0:1], 15
	v_readlane_b32 s58, v254, 15
	v_readlane_b32 s59, v254, 16
	v_bfe_u32 v167, v164, 5, 1
	s_add_u32 s6, s58, s6
	v_and_b32_e32 v168, 31, v164
	s_addc_u32 s7, s59, s7
	v_lshlrev_b32_e32 v140, 9, v167
	v_lshl_add_u64 v[2:3], s[6:7], 0, v[140:141]
	v_lshlrev_b32_e32 v140, 4, v168
	v_lshl_add_u64 v[94:95], v[2:3], 0, v[140:141]
	v_add_co_u32_e32 v2, vcc, s47, v94
	s_movk_i32 s6, 0x7000
	s_nop 0
	v_addc_co_u32_e32 v3, vcc, 0, v95, vcc
	s_waitcnt vmcnt(1)
	v_add_co_u32_e32 v110, vcc, s48, v94
	global_load_dwordx4 v[90:93], v[94:95], off nt
	global_load_dwordx4 v[86:89], v[94:95], off offset:1024 nt
	global_load_dwordx4 v[82:85], v[94:95], off offset:2048 nt
	global_load_dwordx4 v[78:81], v[94:95], off offset:3072 nt
	v_addc_co_u32_e32 v111, vcc, 0, v95, vcc
	v_add_co_u32_e32 v4, vcc, s49, v94
	global_load_dwordx4 v[74:77], v[2:3], off offset:1024 nt
	global_load_dwordx4 v[70:73], v[2:3], off offset:2048 nt
	global_load_dwordx4 v[66:69], v[110:111], off nt
	global_load_dwordx4 v[62:65], v[110:111], off offset:1024 nt
	global_load_dwordx4 v[58:61], v[110:111], off offset:2048 nt
	global_load_dwordx4 v[54:57], v[110:111], off offset:3072 nt
	v_addc_co_u32_e32 v5, vcc, 0, v95, vcc
	v_add_co_u32_e32 v6, vcc, s50, v94
	s_add_u32 s8, s4, 0x4000
	s_nop 0
	v_addc_co_u32_e32 v7, vcc, 0, v95, vcc
	v_add_co_u32_e32 v96, vcc, s51, v94
	global_load_dwordx4 v[122:125], v[2:3], off offset:3072 nt
	global_load_dwordx4 v[26:29], v[4:5], off offset:1024 nt
	global_load_dwordx4 v[22:25], v[4:5], off offset:2048 nt
	global_load_dwordx4 v[18:21], v[4:5], off offset:3072 nt
	global_load_dwordx4 v[106:109], v[6:7], off offset:-4096 nt
	global_load_dwordx4 v[50:53], v[6:7], off nt
	global_load_dwordx4 v[46:49], v[6:7], off offset:1024 nt
	global_load_dwordx4 v[42:45], v[6:7], off offset:2048 nt
	v_addc_co_u32_e32 v97, vcc, 0, v95, vcc
	s_waitcnt vmcnt(18)
	v_add_co_u32_e32 v38, vcc, s24, v94
	s_movk_i32 s4, 0x17f
	s_nop 0
	v_addc_co_u32_e32 v39, vcc, 0, v95, vcc
	global_load_dwordx4 v[114:117], v[6:7], off offset:3072 nt
	global_load_dwordx4 v[14:17], v[38:39], off offset:-4096 nt
	global_load_dwordx4 v[10:13], v[96:97], off offset:1024 nt
	s_nop 0
	global_load_dwordx4 v[6:9], v[96:97], off offset:2048 nt
	global_load_dwordx4 v[2:5], v[38:39], off nt
	global_load_dwordx4 v[30:33], v[38:39], off offset:1024 nt
	global_load_dwordx4 v[34:37], v[38:39], off offset:2048 nt
	s_nop 0
	global_load_dwordx4 v[38:41], v[38:39], off offset:3072 nt
	v_add_co_u32_e32 v112, vcc, s6, v94
	s_addc_u32 s9, s5, 0
	s_nop 0
	v_addc_co_u32_e32 v113, vcc, 0, v95, vcc
	global_load_dwordx4 v[118:121], v[96:97], off offset:3072 nt
	s_nop 0
	global_load_dwordx4 v[94:97], v[112:113], off nt
	global_load_dwordx4 v[98:101], v[112:113], off offset:1024 nt
	global_load_dwordx4 v[102:105], v[112:113], off offset:2048 nt
	global_load_dwordx4 v[126:129], v[110:111], off offset:-4096 nt
	s_nop 0
	global_load_dwordx4 v[110:113], v[112:113], off offset:3072 nt
	v_cmp_lt_i32_e32 vcc, s4, v164
	v_readlane_b32 s53, v254, 10
	v_readlane_b32 s54, v254, 11
	v_readlane_b32 s55, v254, 12
	v_readlane_b32 s56, v254, 13
	v_readlane_b32 s57, v254, 14
	v_readlane_b32 s60, v254, 17
	v_readlane_b32 s61, v254, 18
	v_readlane_b32 s62, v254, 19
	v_readlane_b32 s63, v254, 20
	v_readlane_b32 s64, v254, 21
	v_readlane_b32 s65, v254, 22
	v_readlane_b32 s66, v254, 23
	v_readlane_b32 s67, v254, 24
	s_and_saveexec_b64 s[4:5], vcc
	s_xor_b64 s[4:5], exec, s[4:5]
	s_cbranch_execz .LBB0_893
	s_movk_i32 s6, 0x1a0
	v_cmp_gt_u32_e32 vcc, s6, v164
	s_and_saveexec_b64 s[6:7], vcc
	s_cbranch_execz .LBB0_892
	v_and_or_b32 v130, v164, 3, s8
	v_mov_b32_e32 v131, s9
	v_lshlrev_b64 v[130:131], 7, v[130:131]
	v_add_u32_e32 v132, 0xfffffe80, v164
	v_lshl_add_u64 v[130:131], s[20:21], 0, v[130:131]
	s_lshl_b32 s18, s10, 2
	v_lshrrev_b32_e32 v133, 2, v132
	v_and_b32_e32 v140, -4, v132
	v_lshl_add_u64 v[130:131], v[130:131], 0, s[18:19]
	v_lshl_add_u64 v[130:131], v[130:131], 0, v[140:141]
	v_add_u32_e32 v140, s10, v133
	global_load_dword v132, v[130:131], off
	v_lshl_add_u64 v[130:131], v[140:141], 2, s[76:77]
	global_load_dword v130, v[130:131], off
	s_mov_b32 s10, 0x41a00000
	s_waitcnt vmcnt(0)
	v_add_f32_e32 v130, v132, v130
	v_cmp_nlt_f32_e32 vcc, s10, v130
	s_and_saveexec_b64 s[10:11], vcc
	s_cbranch_execz .LBB0_891
	v_mul_f32_e32 v130, 0x3fb8aa3b, v130
	v_exp_f32_e32 v139, v130
	s_mov_b32 s12, 0x3f2aaaab
	v_add_f32_e32 v132, 1.0, v139
	v_frexp_mant_f32_e32 v134, v132
	v_cvt_f64_f32_e32 v[130:131], v132
	v_frexp_exp_i32_f64_e32 v130, v[130:131]
	v_cmp_gt_f32_e32 vcc, s12, v134
	v_add_f32_e32 v133, -1.0, v132
	v_sub_f32_e32 v135, v133, v132
	v_subbrev_co_u32_e32 v140, vcc, 0, v130, vcc
	v_sub_u32_e32 v130, 0, v140
	v_sub_f32_e32 v133, v139, v133
	v_add_f32_e32 v135, 1.0, v135
	v_ldexp_f32 v131, v132, v130
	v_add_f32_e32 v133, v133, v135
	v_add_f32_e32 v132, -1.0, v131
	v_add_f32_e32 v134, 1.0, v131
	v_ldexp_f32 v130, v133, v130
	v_add_f32_e32 v133, 1.0, v132
	v_add_f32_e32 v135, -1.0, v134
	v_sub_f32_e32 v133, v131, v133
	v_sub_f32_e32 v131, v131, v135
	v_add_f32_e32 v133, v130, v133
	v_add_f32_e32 v130, v130, v131
	v_add_f32_e32 v143, v134, v130
	v_rcp_f32_e32 v145, v143
	v_sub_f32_e32 v131, v143, v134
	v_sub_f32_e32 v144, v130, v131
	v_add_f32_e32 v131, v132, v133
	v_mul_f32_e32 v147, v131, v145
	v_sub_f32_e32 v130, v131, v132
	v_mul_f32_e32 v132, v143, v147
	v_fma_f32 v134, v147, v143, -v132
	v_fmac_f32_e32 v134, v147, v144
	v_sub_f32_e32 v146, v133, v130
	v_add_f32_e32 v130, v132, v134
	v_sub_f32_e32 v133, v131, v130
	v_pk_add_f32 v[136:137], v[130:131], v[132:133] neg_lo:[0,1] neg_hi:[0,1]
	v_mov_b32_e32 v135, v130
	v_pk_add_f32 v[130:131], v[136:137], v[134:135] neg_lo:[0,1] neg_hi:[0,1]
	s_mov_b32 s12, 0x3f317218
	v_add_f32_e32 v131, v146, v131
	v_add_f32_e32 v130, v130, v131
	v_add_f32_e32 v131, v133, v130
	v_mul_f32_e32 v146, v145, v131
	v_mul_f32_e32 v132, v143, v146
	v_fma_f32 v134, v146, v143, -v132
	v_fmac_f32_e32 v134, v146, v144
	v_sub_f32_e32 v133, v133, v131
	v_add_f32_e32 v143, v130, v133
	v_add_f32_e32 v130, v132, v134
	v_sub_f32_e32 v133, v131, v130
	v_pk_add_f32 v[136:137], v[130:131], v[132:133] neg_lo:[0,1] neg_hi:[0,1]
	v_mov_b32_e32 v135, v130
	v_pk_add_f32 v[130:131], v[136:137], v[134:135] neg_lo:[0,1] neg_hi:[0,1]
	s_nop 0
	v_add_f32_e32 v131, v143, v131
	v_add_f32_e32 v130, v130, v131
	v_add_f32_e32 v131, v147, v146
	v_add_f32_e32 v130, v133, v130
	v_sub_f32_e32 v132, v131, v147
	v_mul_f32_e32 v130, v145, v130
	v_sub_f32_e32 v132, v146, v132
	v_add_f32_e32 v132, v132, v130
	v_add_f32_e32 v134, v131, v132
	v_mul_f32_e32 v135, v134, v134
	v_fmamk_f32 v130, v135, 0x3e9b6dac, v158
	v_fmaak_f32 v143, v135, v130, 0x3f2aaada
	v_cvt_f32_i32_e32 v130, v140
	v_sub_f32_e32 v131, v134, v131
	v_sub_f32_e32 v131, v132, v131
	v_ldexp_f32 v136, v131, 1
	v_mul_f32_e32 v131, v134, v135
	v_ldexp_f32 v133, v134, 1
	v_pk_mul_f32 v[134:135], v[130:131], v[142:143]
	s_nop 0
	v_fma_f32 v132, v130, s12, -v134
	v_fmac_f32_e32 v132, 0xb102e308, v130
	v_pk_add_f32 v[130:131], v[134:135], v[132:133]
	s_mov_b32 s12, 0x7f800000
	v_sub_f32_e32 v133, v131, v133
	v_sub_f32_e32 v133, v135, v133
	v_add_f32_e32 v137, v136, v133
	v_mov_b32_e32 v136, v134
	v_pk_add_f32 v[134:135], v[130:131], v[134:135] neg_lo:[0,1] neg_hi:[0,1]
	v_pk_add_f32 v[144:145], v[130:131], v[136:137]
	v_mov_b32_e32 v133, v130
	v_mov_b32_e32 v135, v145
	v_pk_add_f32 v[146:147], v[132:133], v[134:135] neg_lo:[0,1] neg_hi:[0,1]
	v_pk_add_f32 v[132:133], v[132:133], v[134:135]
	v_mov_b32_e32 v136, v137
	v_pk_add_f32 v[134:135], v[132:133], v[130:131] op_sel:[1,0] op_sel_hi:[0,1] neg_lo:[0,1] neg_hi:[0,1]
	v_pk_add_f32 v[148:149], v[144:145], v[134:135] op_sel_hi:[1,0] neg_lo:[0,1] neg_hi:[0,1]
	v_mov_b32_e32 v144, v145
	v_mov_b32_e32 v145, v133
	v_pk_mov_b32 v[134:135], v[130:131], v[134:135] op_sel:[1,0]
	v_mov_b32_e32 v137, v130
	v_pk_add_f32 v[134:135], v[144:145], v[134:135] neg_lo:[0,1] neg_hi:[0,1]
	v_mov_b32_e32 v148, v146
	v_pk_add_f32 v[130:131], v[136:137], v[134:135] neg_lo:[0,1] neg_hi:[0,1]
	v_mov_b32_e32 v147, v133
	v_pk_add_f32 v[134:135], v[148:149], v[130:131]
	v_cmp_neq_f32_e32 vcc, s12, v139
	v_pk_add_f32 v[136:137], v[134:135], v[134:135] op_sel:[0,1] op_sel_hi:[1,0]
	s_mov_b32 s12, 0x33800000
	v_pk_add_f32 v[132:133], v[132:133], v[136:137] op_sel:[1,0] op_sel_hi:[0,1]
	v_mov_b32_e32 v135, v132
	v_pk_add_f32 v[144:145], v[134:135], v[146:147] neg_lo:[0,1] neg_hi:[0,1]
	v_mov_b32_e32 v131, v136
	v_sub_f32_e32 v133, v134, v144
	v_pk_add_f32 v[130:131], v[130:131], v[144:145] neg_lo:[0,1] neg_hi:[0,1]
	v_sub_f32_e32 v133, v146, v133
	v_add_f32_e32 v130, v130, v133
	v_add_f32_e32 v130, v130, v131
	v_add_f32_e32 v130, v132, v130
	v_cndmask_b32_e32 v130, v159, v130, vcc
	v_cmp_ngt_f32_e32 vcc, -1.0, v139
	s_nop 1
	v_cndmask_b32_e32 v130, v160, v130, vcc
	v_cmp_neq_f32_e32 vcc, -1.0, v139
	s_nop 1
	v_cndmask_b32_e32 v130, v161, v130, vcc
	v_cmp_lt_f32_e64 vcc, |v139|, s12
	s_nop 1
	v_cndmask_b32_e32 v130, v130, v139, vcc
